# v086 + row passes use a wave-major global wave id (wave*256 + block) so the 512 extra context rows of the 16896-row passes land on two waves of every workgroup instead of all waves of workgroups 0..63
# speedup vs baseline: 1.0038x; 1.0009x over previous
; #define LAS __attribute__((address_space(3)))
; __device__ __forceinline__ void p0_weights(KAP a, LAS unsigned char* lds, int gw, int NGW, int wave, int lane) {
;     LAS float* scr = (LAS float*)(lds + wave * 8704);
;     unsigned char* ws = a->ws;
;     constexpr int I_TOTAL = (2048 / 64) * (2624 / 32) + (512 / 64) * (1536 / 32) + (512 / 64) * (2048 / 32) + 2 * (2048 / 64) * (2048 / 32) + (2048 / 64) * (4608 / 32)
;                           + 4 * (2048 / 64) * (DFF / 32) + 2 * (DFF / 64) * (2048 / 32);
;     for (int item = gw; item < I_TOTAL; item += NGW) {
;         int it = item;
;         if (conv_matrix(it, a->in[13], 2048, 2624, (bf16*)(ws + WS_WIN0), 0, scr, lane)) continue;
.LBB0_36:
	v_mbcnt_lo_u32_b32 v2, -1, 0
	v_mbcnt_hi_u32_b32 v2, -1, v2
	s_lshl_b32 s5, s87, 3
	v_add_u32_e32 v0, s93, v2
	s_lshl_b32 s33, s74, 3
	v_readfirstlane_b32 s4, v0
	s_ashr_i32 s6, s4, 6
	s_add_i32 s99, s6, s5
	v_writelane_b32 v253, s87, 2
	s_mov_b64 s[4:5], s[0:1]
	s_cmp_gt_i32 s99, 0x71bf
	s_cbranch_scc1 .LBB0_119
	s_load_dwordx2 s[8:9], s[4:5], 0xf0
	v_bfe_u32 v0, v2, 5, 1
	v_and_b32_e32 v28, 31, v2
	v_bfe_u32 v1, v2, 3, 3
	v_lshlrev_b32_e32 v2, 3, v2
	v_and_b32_e32 v2, 56, v2
	v_mov_b32_e32 v3, 0
	v_mul_u32_u24_e32 v6, 0x84, v2
	v_lshlrev_b32_e32 v2, 1, v2
	s_mul_i32 s10, s6, 0x2200
	s_waitcnt lgkmcnt(0)
	v_lshl_add_u64 v[22:23], s[8:9], 0, v[2:3]
	s_mov_b64 s[6:7], 0x100000
	s_add_i32 s11, s10, 0
	v_lshl_add_u64 v[4:5], v[22:23], 0, s[6:7]
	v_lshlrev_b32_e32 v2, 2, v1
	s_mov_b64 s[6:7], 0xc00000
	v_add3_u32 v44, s11, v6, v2
	v_lshl_add_u64 v[6:7], v[22:23], 0, s[6:7]
	s_mov_b64 s[6:7], 0xe00000
	v_lshl_add_u64 v[8:9], v[22:23], 0, s[6:7]
	s_mov_b64 s[6:7], 0x1000000
	v_lshl_add_u64 v[10:11], v[22:23], 0, s[6:7]
	s_mov_b64 s[6:7], 0x1800000
	v_lshl_add_u64 v[12:13], v[22:23], 0, s[6:7]
	s_mov_b64 s[6:7], 0x2a00000
	v_lshl_add_u64 v[14:15], v[22:23], 0, s[6:7]
	s_mov_b64 s[6:7], 0x3200000
	v_lshl_add_u64 v[16:17], v[22:23], 0, s[6:7]
	s_mov_b64 s[6:7], 0x5e00000
	v_lshl_add_u64 v[18:19], v[22:23], 0, s[6:7]
	s_mov_b64 s[6:7], 0x8a00000
	v_mul_u32_u24_e32 v2, 0x84, v0
	v_lshl_add_u64 v[20:21], v[22:23], 0, s[6:7]
	s_mov_b64 s[6:7], 0xa000000
	v_or_b32_e32 v2, s10, v2
	v_lshlrev_b32_e32 v24, 2, v28
	v_or_b32_e32 v45, 8, v1
	v_or_b32_e32 v46, 16, v1
	v_or_b32_e32 v47, 24, v1
	v_lshl_add_u64 v[22:23], v[22:23], 0, s[6:7]
	v_add3_u32 v48, v2, v24, 0
	v_mov_b32_e32 v25, v3
	v_or_b32_e32 v49, 14, v0
	v_or_b32_e32 v50, 12, v0
	v_or_b32_e32 v51, 10, v0
	v_or_b32_e32 v52, 8, v0
	v_or_b32_e32 v53, 6, v0
	v_or_b32_e32 v54, 4, v0
	v_or_b32_e32 v55, 2, v0
	v_or_b32_e32 v26, 0x2c00000, v24
	v_mov_b32_e32 v27, v3
	s_movk_i32 s23, 0x2900
	s_movk_i32 s24, 0x7fff
	s_mov_b32 s25, 0xffff0000
	s_movk_i32 s26, 0x1800
	s_movk_i32 s27, 0x4800
	s_movk_i32 s28, 0x1600
	s_movk_i32 s29, 0x5800
	s_mov_b64 s[6:7], 0x2c00000
	v_lshlrev_b32_e32 v2, 2, v28
	v_mov_b32_e32 v56, 0x4800
	v_mov_b32_e32 v57, 0x5800
	s_branch .LBB0_39

; #define LAS __attribute__((address_space(3)))
; __device__ __forceinline__ void pass_pre(const float* hlat, const float* hctx, const float* g, const float* mod, int sh_off, int sc_off, bf16* U, int nrows, int gw, int NGW, int lane, LAS float* lp, int tid) {
;     lds_vec(lp + 2048, g, tid);
; #pragma unroll
;     for (int vi = 0; vi < 3; ++vi) { lds_vec(lp + 4096 + (3 * vi + 1) * 2048, mod + vi * 12288 + sh_off, tid); lds_vec(lp + 4096 + (3 * vi + 2) * 2048, mod + vi * 12288 + sc_off, tid); }
;     __syncthreads();
;     for (int m0 = gw; m0 < nrows; m0 += 2 * NGW) {
;         int mr[2]; mr[0] = m0; mr[1] = m0 + NGW; const bool two = mr[1] < nrows; if (!two) mr[1] = m0;
;         f32x4 v[2][8]; float ss[2];
; #pragma unroll
;         for (int r = 0; r < 2; ++r) { const int m = mr[r]; const float* src = m < MLAT ? hlat + (size_t)m * DM : hctx + (size_t)(m - MLAT) * DM;
; #pragma unroll
;             for (int j = 0; j < 8; ++j) v[r][j] = *(const f32x4*)(src + 256 * j + 4 * lane); }
.LBB0_171:
	s_or_b64 exec, exec, s[16:17]
	s_mov_b64 s[18:19], s[0:1]
	s_mov_b64 s[20:21], s[0:1]
	s_mov_b64 s[2:3], s[0:1]
	s_waitcnt lgkmcnt(0)
	s_barrier
	v_mbcnt_lo_u32_b32 v32, -1, 0
	v_mbcnt_hi_u32_b32 v32, -1, v32
	s_mov_b64 s[4:5], s[0:1]
	s_load_dwordx2 s[2:3], s[2:3], 0x30
	s_load_dwordx2 s[4:5], s[4:5], 0xf0
	v_add_u32_e32 v28, s93, v32
	v_lshlrev_b32_e32 v0, 2, v28
	v_ashrrev_i32_e32 v1, 31, v0
	v_lshlrev_b64 v[4:5], 2, v[0:1]
	s_waitcnt lgkmcnt(0)
	v_lshl_add_u64 v[0:1], s[2:3], 0, v[4:5]
	v_lshl_add_u64 v[20:21], s[4:5], 0, v[4:5]
	s_movk_i32 s2, 0x2000
	v_add_co_u32_e32 v8, vcc, s2, v20
	s_mov_b32 s2, 0xc000
	s_nop 0
	v_addc_co_u32_e32 v9, vcc, 0, v21, vcc
	v_add_co_u32_e32 v12, vcc, s2, v20
	s_mov_b32 s2, 0xe000
	s_nop 0
	v_addc_co_u32_e32 v13, vcc, 0, v21, vcc
	v_add_co_u32_e32 v16, vcc, s2, v20
	s_mov_b32 s2, 0x18000
	s_nop 0
	v_addc_co_u32_e32 v17, vcc, 0, v21, vcc
	v_add_co_u32_e32 v22, vcc, s2, v20
	s_mov_b64 s[22:23], s[0:1]
	s_nop 0
	v_addc_co_u32_e32 v23, vcc, 0, v21, vcc
	v_add_co_u32_e32 v24, vcc, 0x1a000, v20
	global_load_dwordx4 v[0:3], v[0:1], off
	s_nop 0
	v_addc_co_u32_e32 v25, vcc, 0, v21, vcc
	global_load_dwordx4 v[4:7], v[20:21], off
	s_nop 0
	global_load_dwordx4 v[8:11], v[8:9], off
	s_nop 0
	global_load_dwordx4 v[12:15], v[12:13], off
	s_nop 0
	global_load_dwordx4 v[16:19], v[16:17], off
	s_nop 0
	global_load_dwordx4 v[20:23], v[22:23], off
	s_nop 0
	global_load_dwordx4 v[24:27], v[24:25], off
	v_readfirstlane_b32 s2, v28
	s_ashr_i32 s2, s2, 6
	v_readlane_b32 s3, v253, 2
	s_lshl_b32 s98, s2, 8
	s_add_i32 s16, s98, s3
	v_lshl_add_u32 v28, v28, 4, 0
	s_cmpk_lt_i32 s16, 0x4200
	v_add_u32_e32 v29, 0x12000, v28
	v_add_u32_e32 v30, 0x14000, v28
	s_waitcnt vmcnt(6)
	ds_write_b128 v28, v[0:3] offset:8192
	s_waitcnt vmcnt(5)
	ds_write_b128 v28, v[4:7] offset:24576
	s_waitcnt vmcnt(4)
	ds_write_b128 v28, v[8:11] offset:32768
	s_waitcnt vmcnt(3)
	ds_write_b128 v28, v[12:15] offset:49152
	s_waitcnt vmcnt(2)
	ds_write_b128 v28, v[16:19] offset:57344
	s_waitcnt vmcnt(1)
	ds_write_b128 v29, v[20:23]
	s_waitcnt vmcnt(0)
	ds_write_b128 v30, v[24:27]
	s_waitcnt lgkmcnt(0)
	s_barrier
	s_cbranch_scc0 .LBB0_176
	v_lshlrev_b32_e32 v0, 2, v32
	v_and_b32_e32 v34, 0xfc, v0
	v_bfrev_b32_e32 v1, 0.5
	s_movk_i32 s4, 0x80
	v_lshl_add_u32 v77, v34, 2, 0
	s_load_dwordx2 s[18:19], s[18:19], 0x0
	s_nop 0
	s_load_dwordx2 s[20:21], s[20:21], 0x10
	s_nop 0
	s_load_dwordx2 s[2:3], s[22:23], 0xf0
	v_bitop3_b32 v71, v0, 4, v1 bitop3:0x6c
	v_bitop3_b32 v72, v0, 8, v1 bitop3:0x6c
	v_bitop3_b32 v73, v0, 16, v1 bitop3:0x6c
	v_bitop3_b32 v74, v0, 32, v1 bitop3:0x6c
	v_bitop3_b32 v75, v0, 64, v1 bitop3:0x6c
	v_bitop3_b32 v76, v0, s4, v1 bitop3:0x6c
	ds_read_b128 v[0:3], v77 offset:8192
	ds_read_b128 v[4:7], v77 offset:9216
	ds_read_b128 v[8:11], v77 offset:10240
	ds_read_b128 v[12:15], v77 offset:11264
	ds_read_b128 v[16:19], v77 offset:12288
	ds_read_b128 v[20:23], v77 offset:13312
	ds_read_b128 v[24:27], v77 offset:14336
	ds_read_b128 v[28:31], v77 offset:15360
	s_ashr_i32 s17, s16, 31
	v_mov_b32_e32 v65, 0
	s_lshl_b32 s22, s74, 4
	v_lshlrev_b32_e32 v64, 1, v34
	s_lshl_b64 s[6:7], s[16:17], 12
	s_waitcnt lgkmcnt(0)
	v_lshl_add_u64 v[36:37], s[2:3], 0, v[64:65]
	v_and_b32_e32 v32, 63, v32
	s_add_u32 s2, s2, s6
	v_lshlrev_b32_e32 v64, 3, v32
	s_addc_u32 s3, s3, s7
	s_mov_b64 s[4:5], 0xba00000
	v_lshl_add_u64 v[32:33], s[2:3], 0, v[64:65]
	s_ashr_i32 s23, s22, 31
	v_lshl_add_u64 v[66:67], v[36:37], 0, s[4:5]
	v_lshl_add_u64 v[68:69], v[32:33], 0, s[4:5]
	s_lshl_b64 s[24:25], s[22:23], 12
	s_mov_b64 s[26:27], 0
	v_lshlrev_b32_e32 v64, 2, v34
	s_movk_i32 s2, 0x1000
	v_mov_b32_e32 v78, 0x358637bd
	s_mov_b32 s3, 0x800000
	s_movk_i32 s4, 0x7fff
	s_mov_b32 s5, 0xffff0000
	s_mov_b32 s34, s16
	s_branch .LBB0_174

; __device__ __forceinline__ void head_gain16(float (&ga)[8], float (&gb)[8], const float* gain, int lane) {
;     const int sub = lane & 7, ca = 8 * (sub >> 2) + (sub & 3);
; #pragma unroll
;     for (int i = 0; i < 8; ++i) { ga[i] = gain[ca * 8 + i]; gb[i] = gain[(ca + 4) * 8 + i]; }
; }
; __device__ __forceinline__ void prep_cd(bf16* P, const float* cqn, const float* ckn, const float* dqn, const float* dkn, int gw, int NGW, int lane) {
;     float gca[8], gcb[8], gda[8], gdb[8]; head_gain16(gca, gcb, ckn, lane); head_gain16(gda, gdb, dkn, lane);
;     for (int m = gw; m < MALL; m += NGW) {
;         bf16* row = P + (size_t)m * N_IN1; const bool lat = m < MLAT; const int t = m & (SEQ - 1); const float pr = (float)(t >> 6), pc = (float)(t & 63);
;         float cs[8], sn[8];
; #pragma unroll
;         for (int i = 0; i < 8; ++i) { cs[i] = 1.f; sn[i] = 0.f; }
;         heads8<false>(row + 2560, true, gda, gdb, cs, sn, lane);
;         if (lat) { rope_tab8(cs, sn, pr, pc, lane); heads8<true>(row + 1024, lane < 16, gca, gcb, cs, sn, lane); }
.LBB0_313:
	s_or_b64 exec, exec, s[16:17]
	v_readlane_b32 s4, v254, 52
	v_readlane_b32 s5, v254, 53
	s_mov_b64 s[16:17], -1
	s_and_b64 vcc, exec, s[4:5]
	s_waitcnt lgkmcnt(0)
	s_barrier
	s_cbranch_vccz .LBB0_565
	s_waitcnt vmcnt(12)
	v_mbcnt_lo_u32_b32 v32, -1, 0
	v_mbcnt_hi_u32_b32 v32, -1, v32
	v_readlane_b32 s4, v253, 2
	v_add_u32_e32 v0, s93, v32
	s_mov_b64 s[16:17], s[0:1]
	v_readfirstlane_b32 s2, v0
	s_ashr_i32 s2, s2, 6
	s_lshl_b32 s2, s2, 8
	s_add_i32 s2, s2, s4
	s_mov_b64 s[4:5], s[0:1]
	s_mov_b64 s[20:21], s[0:1]
	s_mov_b64 s[4:5], s[0:1]
	s_mov_b64 s[18:19], s[0:1]
	s_cmpk_gt_i32 s2, 0x41ff
	s_cbranch_scc1 .LBB0_329
	s_load_dwordx2 s[4:5], s[20:21], 0xc0
	v_lshlrev_b32_e32 v0, 1, v32
	v_and_b32_e32 v33, 3, v32
	v_and_or_b32 v0, v0, 8, v33
	v_lshlrev_b32_e32 v28, 5, v0
	s_waitcnt lgkmcnt(0)
	global_load_dwordx4 v[0:3], v28, s[4:5] offset:128
	global_load_dwordx4 v[4:7], v28, s[4:5]
	global_load_dwordx4 v[8:11], v28, s[4:5] offset:144
	s_load_dwordx2 s[6:7], s[18:19], 0xd8
	v_and_b32_e32 v34, 63, v32
	v_lshlrev_b32_e32 v36, 3, v32
	global_load_dwordx4 v[12:15], v28, s[4:5] offset:16
	s_waitcnt lgkmcnt(0)
	global_load_dwordx4 v[16:19], v28, s[6:7] offset:128
	global_load_dwordx4 v[20:23], v28, s[6:7] offset:144
	global_load_dwordx4 v[24:27], v28, s[6:7]
	s_nop 0
	global_load_dwordx4 v[28:31], v28, s[6:7] offset:16
	v_and_b32_e32 v35, 4, v32
	v_lshlrev_b32_e32 v37, 2, v34
	v_cmp_gt_u32_e64 s[38:39], 16, v34
	v_and_b32_e32 v34, 24, v36
	v_cmp_eq_u32_e64 s[40:41], 0, v35
	s_waitcnt vmcnt(16)
	v_xor_b32_e32 v50, 4, v37
	v_xor_b32_e32 v51, 8, v37
	v_xor_b32_e32 v52, 16, v37
	v_cvt_f32_ubyte0_e32 v35, v34
	v_or_b32_e32 v36, 1, v34
	v_or_b32_e32 v37, 2, v34
	v_or_b32_e32 v38, 3, v34
	v_or_b32_e32 v39, 4, v34
	v_or_b32_e32 v40, 5, v34
	v_or_b32_e32 v41, 6, v34
	v_mul_f32_e32 v35, 0xbd000000, v35
	v_cvt_f32_ubyte0_e32 v36, v36
	v_cvt_f32_ubyte0_e32 v37, v37
	v_cvt_f32_ubyte0_e32 v38, v38
	v_cvt_f32_ubyte0_e32 v39, v39
	v_cvt_f32_ubyte0_e32 v40, v40
	v_cvt_f32_ubyte0_e32 v41, v41
	v_or_b32_e32 v34, 7, v34
	v_mul_f32_e32 v35, 0x41549a78, v35
	v_mul_f32_e32 v36, 0xbd000000, v36
	v_mul_f32_e32 v37, 0xbd000000, v37
	v_mul_f32_e32 v38, 0xbd000000, v38
	v_mul_f32_e32 v39, 0xbd000000, v39
	v_mul_f32_e32 v40, 0xbd000000, v40
	v_mul_f32_e32 v41, 0xbd000000, v41
	s_load_dwordx2 s[16:17], s[16:17], 0xf0
	v_cvt_f32_ubyte0_e32 v34, v34
	v_exp_f32_e32 v53, v35
	v_mul_f32_e32 v35, 0x41549a78, v36
	v_mul_f32_e32 v36, 0x41549a78, v37
	v_mul_f32_e32 v37, 0x41549a78, v38
	v_mul_f32_e32 v38, 0x41549a78, v39
	v_mul_f32_e32 v39, 0x41549a78, v40
	v_mul_f32_e32 v40, 0x41549a78, v41
	v_mul_f32_e32 v34, 0xbd000000, v34
	v_exp_f32_e32 v59, v40
	v_mul_f32_e32 v34, 0x41549a78, v34
	v_exp_f32_e32 v57, v38
	v_exp_f32_e32 v54, v35
	v_exp_f32_e32 v55, v36
	v_exp_f32_e32 v56, v37
	v_exp_f32_e32 v58, v39
	v_exp_f32_e32 v60, v34
	s_waitcnt vmcnt(7)
	v_mov_b32_e32 v38, v1
	s_waitcnt vmcnt(6)
	v_mov_b32_e32 v40, v5
	v_mov_b32_e32 v5, v6
	s_waitcnt vmcnt(4)
	v_mov_b32_e32 v6, v13
	v_mov_b32_e32 v13, v14
	s_waitcnt vmcnt(2)
	v_mov_b32_e32 v14, v21
	v_mov_b32_e32 v21, v22
	s_waitcnt vmcnt(0)
	v_mov_b32_e32 v22, v29
	v_mov_b32_e32 v29, v30
	v_lshlrev_b32_e32 v30, 5, v32
	v_mov_b32_e32 v1, v2
	v_mov_b32_e32 v2, v9
	v_mov_b32_e32 v9, v10
	v_mov_b32_e32 v10, v17
	v_mov_b32_e32 v17, v18
	v_mov_b32_e32 v18, v25
	v_mov_b32_e32 v25, v26
	v_and_b32_e32 v194, 0x700, v30
	v_mov_b32_e32 v26, 0x2400
	v_mov_b32_e32 v39, v3
	v_mov_b32_e32 v41, v7
	v_mov_b32_e32 v3, v11
	v_mov_b32_e32 v7, v15
	v_mov_b32_e32 v11, v19
	v_mov_b32_e32 v15, v23
	v_mov_b32_e32 v19, v27
	v_mov_b32_e32 v23, v31
	v_mad_i64_i32 v[26:27], s[4:5], s2, v26, v[194:195]
	v_lshlrev_b32_e32 v31, 4, v33
	v_and_b32_e32 v30, 0x80, v30
	v_or3_b32 v26, v30, v31, v26
	s_waitcnt lgkmcnt(0)
	v_lshl_add_u64 v[26:27], s[16:17], 0, v[26:27]
	s_mov_b64 s[4:5], 0x13e01400
	v_lshl_add_u64 v[26:27], v[26:27], 0, s[4:5]
	s_branch .LBB0_318

; __device__ __forceinline__ void head_gain16(float (&ga)[8], float (&gb)[8], const float* gain, int lane) {
;     const int sub = lane & 7, ca = 8 * (sub >> 2) + (sub & 3);
; #pragma unroll
;     for (int i = 0; i < 8; ++i) { ga[i] = gain[ca * 8 + i]; gb[i] = gain[(ca + 4) * 8 + i]; }
; }
; __device__ __forceinline__ void prep_ab(bf16* P, const float* aqn, const float* akn, const float* bqn, const float* bkvn, int gw, int NGW, int lane) {
;     float ga[8], gb[8]; head_gain16(ga, gb, akn, lane);
;     const f32x4 q0 = *(const f32x4*)(bqn + 8 * lane), q1 = *(const f32x4*)(bqn + 8 * lane + 4), k0 = *(const f32x4*)(bkvn + 8 * lane), k1 = *(const f32x4*)(bkvn + 8 * lane + 4);
;     for (int m = gw; m < MALL; m += NGW) {
;         bf16* row = P + (size_t)m * N_IN0; const bool lat = m < MLAT; const int t = m & (SEQ - 1); const float pr = (float)(t >> 6), pc = (float)(t & 63);
;         float c1[8], c2[8];
;         unpack8(*(const v4u*)(row + 1536 + 8 * lane), c1); unpack8(*(const v4u*)(row + 2048 + 8 * lane), c2);
;         if (lat && lane < 32) rope64(row + 2560, pr, pc, lane);
;         float cs[8], sn[8];
;         if (lat) { rope_tab8(cs, sn, pr, pc, lane); heads8<true>(row + 1024, lane < 16, ga, gb, cs, sn, lane); }
.LBB0_565:
	s_and_b64 vcc, exec, s[16:17]
	s_cbranch_vccz .LBB0_797
	s_waitcnt vmcnt(12)
	v_mbcnt_lo_u32_b32 v32, -1, 0
	v_mbcnt_hi_u32_b32 v32, -1, v32
	v_readlane_b32 s4, v253, 2
	v_add_u32_e32 v0, s93, v32
	s_mov_b64 s[16:17], s[0:1]
	v_readfirstlane_b32 s2, v0
	s_ashr_i32 s2, s2, 6
	s_lshl_b32 s2, s2, 8
	s_add_i32 s2, s2, s4
	s_mov_b64 s[4:5], s[0:1]
	s_mov_b64 s[18:19], s[0:1]
	s_mov_b64 s[20:21], s[0:1]
	s_mov_b64 s[38:39], s[0:1]
	s_cmpk_gt_i32 s2, 0x41ff
	s_cbranch_scc1 .LBB0_583
	s_load_dwordx2 s[4:5], s[20:21], 0x88
	s_load_dwordx2 s[6:7], s[38:39], 0x90
	v_and_b32_e32 v33, 63, v32
	v_lshlrev_b32_e32 v12, 5, v33
	v_and_b32_e32 v34, 3, v32
	s_waitcnt lgkmcnt(0)
	global_load_dwordx4 v[0:3], v12, s[4:5]
	global_load_dwordx4 v[4:7], v12, s[4:5] offset:16
	global_load_dwordx4 v[8:11], v12, s[6:7] offset:16
	s_nop 0
	global_load_dwordx4 v[12:15], v12, s[6:7]
	s_load_dwordx2 s[4:5], s[18:19], 0x80
	v_lshlrev_b32_e32 v35, 1, v33
	v_and_or_b32 v16, v35, 8, v34
	v_lshlrev_b32_e32 v28, 5, v16
	s_waitcnt lgkmcnt(0)
	global_load_dwordx4 v[16:19], v28, s[4:5] offset:128
	global_load_dwordx4 v[20:23], v28, s[4:5]
	global_load_dwordx4 v[24:27], v28, s[4:5] offset:144
	s_nop 0
	global_load_dwordx4 v[28:31], v28, s[4:5] offset:16
	v_lshlrev_b32_e32 v36, 3, v32
	v_and_b32_e32 v37, 15, v32
	v_and_b32_e32 v38, 4, v32
	v_cvt_f32_ubyte0_e32 v39, v37
	v_and_b32_e32 v36, 24, v36
	v_lshlrev_b32_e32 v40, 2, v33
	v_cmp_eq_u32_e64 s[42:43], 0, v38
	v_mul_f32_e32 v38, 0xbd800000, v39
	v_cvt_f32_ubyte0_e32 v39, v36
	v_or_b32_e32 v41, 1, v36
	v_or_b32_e32 v42, 2, v36
	v_or_b32_e32 v43, 3, v36
	v_or_b32_e32 v44, 4, v36
	v_or_b32_e32 v45, 5, v36
	v_or_b32_e32 v46, 6, v36
	v_or_b32_e32 v36, 7, v36
	s_load_dwordx2 s[16:17], s[16:17], 0xf0
	v_xor_b32_e32 v66, 4, v40
	v_xor_b32_e32 v67, 8, v40
	v_xor_b32_e32 v68, 16, v40
	v_xor_b32_e32 v69, 32, v40
	v_xor_b32_e32 v70, 64, v40
	v_xor_b32_e32 v71, 0x80, v40
	v_mul_f32_e32 v38, 0x41549a78, v38
	v_mul_f32_e32 v39, 0xbd000000, v39
	v_cvt_f32_ubyte0_e32 v40, v41
	v_cvt_f32_ubyte0_e32 v41, v42
	v_cvt_f32_ubyte0_e32 v42, v43
	v_cvt_f32_ubyte0_e32 v43, v44
	v_cvt_f32_ubyte0_e32 v44, v45
	v_cvt_f32_ubyte0_e32 v45, v46
	v_cvt_f32_ubyte0_e32 v36, v36
	v_exp_f32_e32 v72, v38
	v_mul_f32_e32 v38, 0x41549a78, v39
	v_mul_f32_e32 v39, 0xbd000000, v40
	v_mul_f32_e32 v40, 0xbd000000, v41
	v_mul_f32_e32 v41, 0xbd000000, v42
	v_mul_f32_e32 v42, 0xbd000000, v43
	v_mul_f32_e32 v43, 0xbd000000, v44
	v_mul_f32_e32 v44, 0xbd000000, v45
	v_mul_f32_e32 v36, 0xbd000000, v36
	v_exp_f32_e32 v73, v38
	v_mul_f32_e32 v38, 0x41549a78, v39
	v_mul_f32_e32 v39, 0x41549a78, v40
	v_mul_f32_e32 v40, 0x41549a78, v41
	v_mul_f32_e32 v41, 0x41549a78, v42
	v_mul_f32_e32 v42, 0x41549a78, v43
	v_mul_f32_e32 v43, 0x41549a78, v44
	v_mul_f32_e32 v36, 0x41549a78, v36
	v_exp_f32_e32 v74, v38
	v_exp_f32_e32 v75, v39
	v_exp_f32_e32 v76, v40
	v_exp_f32_e32 v77, v41
	v_exp_f32_e32 v78, v42
	v_exp_f32_e32 v79, v43
	v_exp_f32_e32 v80, v36
	s_movk_i32 s4, 0x80
	s_mul_i32 s5, s2, 0x1600
	s_waitcnt lgkmcnt(0)
	s_add_u32 s16, s16, s5
	v_cmp_gt_u32_e64 s[38:39], 32, v33
	v_cmp_gt_u32_e64 s[40:41], 16, v33
	s_waitcnt vmcnt(16)
	v_mov_b32_e32 v51, v195
	s_waitcnt vmcnt(7)
	v_mov_b32_e32 v46, v1
	v_mov_b32_e32 v47, v3
	v_mov_b32_e32 v1, v2
	s_waitcnt vmcnt(6)
	v_mov_b32_e32 v2, v5
	v_mov_b32_e32 v3, v7
	v_mov_b32_e32 v5, v6
	s_waitcnt vmcnt(4)
	v_mov_b32_e32 v6, v13
	v_mov_b32_e32 v7, v15
	v_mov_b32_e32 v13, v14
	v_mov_b32_e32 v14, v9
	v_mov_b32_e32 v15, v11
	v_mov_b32_e32 v9, v10
	s_waitcnt vmcnt(3)
	v_mov_b32_e32 v10, v17
	v_mov_b32_e32 v11, v19
	v_mov_b32_e32 v17, v18
	s_waitcnt vmcnt(1)
	v_mov_b32_e32 v18, v25
	v_mov_b32_e32 v19, v27
	v_mov_b32_e32 v25, v26
	v_lshlrev_b32_e32 v26, 5, v32
	v_lshlrev_b32_e32 v27, 4, v34
	v_and_or_b32 v27, v26, s4, v27
	s_movk_i32 s4, 0x700
	v_mov_b32_e32 v48, v21
	v_mov_b32_e32 v21, v22
	s_waitcnt vmcnt(0)
	v_mov_b32_e32 v22, v29
	v_mov_b32_e32 v29, v30
	v_and_or_b32 v194, v26, s4, v27
	s_mul_hi_i32 s4, s2, 0x1600
	v_and_or_b32 v30, v35, 32, v37
	v_mov_b32_e32 v49, v23
	v_mov_b32_e32 v23, v31
	s_addc_u32 s17, s17, s4
	v_lshlrev_b32_e32 v26, 4, v33
	v_mov_b32_e32 v27, v195
	v_lshlrev_b32_e32 v50, 1, v30
	s_branch .LBB0_570

; #define LAS __attribute__((address_space(3)))
; __device__ __forceinline__ void pass_post(const bf16* o16, const float* opart, const float* hlat, const float* hctx, const bf16* h16in, float* olat, float* octx, bf16* h16out, const float* gpost, const float* mod, int gt_off, ...
;     lds_vec(lp, gpost, tid); if (U) lds_vec(lp + 2048, gpre, tid);
; #pragma unroll
;     for (int vi = 0; vi < 3; ++vi) { lds_vec(lp + 4096 + (3 * vi) * 2048, mod + vi * 12288 + gt_off, tid);
;         if (U) { lds_vec(lp + 4096 + (3 * vi + 1) * 2048, modu + vi * 12288 + sh_off, tid); lds_vec(lp + 4096 + (3 * vi + 2) * 2048, modu + vi * 12288 + sc_off, tid); } }
;     __syncthreads();
;     for (int m0 = gw; m0 < nrows; m0 += 2 * NGW) {
;         int mr[2]; mr[0] = m0; mr[1] = m0 + NGW; const bool two = mr[1] < nrows; if (!two) mr[1] = m0;
;         f32x4 v[2][8], hh[2][8]; float ss[2];
; #pragma unroll
;         for (int r = 0; r < 2; ++r) { const int m = mr[r]; ss[r] = 0.f;
;             const float* hs = m < MLAT ? hlat + (size_t)m * DM : hctx + (size_t)(m - MLAT) * DM;
;             if (m < MLAT) { const bf16* orow = o16 + (size_t)m * DM;
; #pragma unroll
.LBB0_958:
	s_ashr_i32 s2, s2, 6
	v_readlane_b32 s4, v253, 2
	s_lshl_b32 s98, s2, 8
	s_add_i32 s20, s98, s4
	v_readlane_b32 s4, v254, 54
	v_readlane_b32 s5, v254, 55
	s_and_b64 s[4:5], s[4:5], exec
	s_mov_b64 s[4:5], s[0:1]
	s_mov_b64 s[4:5], s[0:1]
	s_mov_b64 s[52:53], s[0:1]
	s_mov_b64 s[4:5], s[0:1]
	s_load_dwordx2 s[4:5], s[4:5], 0x38
	s_mov_b64 s[6:7], s[0:1]
	s_movk_i32 s2, 0x4200
	s_cselect_b32 s66, s2, 0x4000
	v_readlane_b32 s2, v254, 41
	s_load_dwordx2 s[6:7], s[6:7], 0xf0
	s_mov_b64 s[8:9], s[0:1]
	s_lshl_b32 s30, s2, 11
	s_lshl_b64 s[38:39], s[30:31], 2
	s_load_dwordx2 s[8:9], s[8:9], 0x40
	s_waitcnt lgkmcnt(0)
	s_add_u32 s4, s4, s38
	s_mul_i32 s30, s2, 0x9000
	s_addc_u32 s5, s5, s39
	s_lshl_b64 s[40:41], s[30:31], 2
	s_add_u32 s6, s6, s40
	s_addc_u32 s7, s7, s41
	v_lshlrev_b32_e32 v2, 2, v0
	s_add_u32 s8, s8, s38
	v_writelane_b32 v254, s38, 60
	v_ashrrev_i32_e32 v3, 31, v2
	s_addc_u32 s9, s9, s39
	v_writelane_b32 v254, s39, 61
	s_mov_b64 s[38:39], s[0:1]
	v_lshlrev_b64 v[6:7], 2, v[2:3]
	s_mov_b64 s[54:55], s[0:1]
	v_lshl_add_u64 v[2:3], s[4:5], 0, v[6:7]
	s_load_dwordx2 s[38:39], s[38:39], 0xf0
	global_load_dwordx4 v[2:5], v[2:3], off
	v_lshl_add_u32 v8, v0, 4, 0
	v_lshl_add_u64 v[0:1], s[8:9], 0, v[6:7]
	s_movk_i32 s2, 0x4000
	s_waitcnt lgkmcnt(0)
	s_add_u32 s38, s38, s40
	v_writelane_b32 v199, s40, 11
	s_addc_u32 s39, s39, s41
	s_cmp_ge_i32 s20, s66
	v_writelane_b32 v199, s41, 12
	s_waitcnt vmcnt(0)
	ds_write_b128 v8, v[2:5]
	global_load_dwordx4 v[0:3], v[0:1], off
	v_lshl_add_u64 v[4:5], s[6:7], 0, v[6:7]
	v_lshl_add_u64 v[6:7], s[38:39], 0, v[6:7]
	s_waitcnt vmcnt(0)
	ds_write_b128 v8, v[0:3] offset:8192
	v_add_co_u32_e32 v0, vcc, s2, v4
	s_movk_i32 s2, 0x6000
	s_nop 0
	v_addc_co_u32_e32 v1, vcc, 0, v5, vcc
	global_load_dwordx4 v[0:3], v[0:1], off
	s_waitcnt vmcnt(0)
	ds_write_b128 v8, v[0:3] offset:16384
	v_add_co_u32_e32 v0, vcc, s2, v6
	s_mov_b32 s2, 0x8000
	s_nop 0
	v_addc_co_u32_e32 v1, vcc, 0, v7, vcc
	global_load_dwordx4 v[0:3], v[0:1], off
	s_waitcnt vmcnt(0)
	ds_write_b128 v8, v[0:3] offset:24576
	v_add_co_u32_e32 v0, vcc, s2, v6
	s_mov_b32 s2, 0x10000
	s_nop 0
	v_addc_co_u32_e32 v1, vcc, 0, v7, vcc
	global_load_dwordx4 v[0:3], v[0:1], off
	s_waitcnt vmcnt(0)
	ds_write_b128 v8, v[0:3] offset:32768
	v_add_co_u32_e32 v0, vcc, s2, v4
	s_mov_b32 s2, 0x12000
	s_nop 0
	v_addc_co_u32_e32 v1, vcc, 0, v5, vcc
	global_load_dwordx4 v[0:3], v[0:1], off
	s_waitcnt vmcnt(0)
	ds_write_b128 v8, v[0:3] offset:40960
	v_add_co_u32_e32 v0, vcc, s2, v6
	s_mov_b32 s2, 0x14000
	s_nop 0
	v_addc_co_u32_e32 v1, vcc, 0, v7, vcc
	global_load_dwordx4 v[0:3], v[0:1], off
	s_waitcnt vmcnt(0)
	ds_write_b128 v8, v[0:3] offset:49152
	v_add_co_u32_e32 v0, vcc, s2, v6
	s_mov_b32 s2, 0x1c000
	s_nop 0
	v_addc_co_u32_e32 v1, vcc, 0, v7, vcc
	global_load_dwordx4 v[0:3], v[0:1], off
	s_waitcnt vmcnt(0)
	ds_write_b128 v8, v[0:3] offset:57344
	v_add_co_u32_e32 v0, vcc, s2, v4
	v_add_u32_e32 v4, 0x10000, v8
	s_nop 0
	v_addc_co_u32_e32 v1, vcc, 0, v5, vcc
	global_load_dwordx4 v[0:3], v[0:1], off
	v_add_u32_e32 v5, 0x12000, v8
	s_waitcnt vmcnt(0)
	ds_write_b128 v4, v[0:3]
	v_add_co_u32_e32 v0, vcc, 0x1e000, v6
	v_add_u32_e32 v4, 0x14000, v8
	s_nop 0
	v_addc_co_u32_e32 v1, vcc, 0, v7, vcc
	global_load_dwordx4 v[0:3], v[0:1], off
	s_waitcnt vmcnt(0)
	ds_write_b128 v5, v[0:3]
	v_add_co_u32_e32 v0, vcc, 0x20000, v6
	s_nop 1
	v_addc_co_u32_e32 v1, vcc, 0, v7, vcc
	global_load_dwordx4 v[0:3], v[0:1], off
	s_waitcnt vmcnt(0)
	ds_write_b128 v4, v[0:3]
	s_waitcnt lgkmcnt(0)
	s_barrier
	s_cbranch_scc1 .LBB0_971
	v_lshlrev_b32_e32 v0, 2, v64
	v_and_b32_e32 v192, 0xfc, v0
	v_bfrev_b32_e32 v1, 0.5
	s_movk_i32 s21, 0x80
	v_lshl_add_u32 v221, v192, 2, 0
	s_load_dwordx2 s[4:5], s[52:53], 0xf0
	s_load_dwordx2 s[6:7], s[54:55], 0xf0
	v_bitop3_b32 v193, v0, 4, v1 bitop3:0x6c
	v_bitop3_b32 v205, v0, 8, v1 bitop3:0x6c
	v_bitop3_b32 v207, v0, 16, v1 bitop3:0x6c
	v_bitop3_b32 v209, v0, 32, v1 bitop3:0x6c
	v_bitop3_b32 v219, v0, 64, v1 bitop3:0x6c
	v_bitop3_b32 v220, v0, s21, v1 bitop3:0x6c
	ds_read_b128 v[0:3], v221
	ds_read_b128 v[4:7], v221 offset:1024
	ds_read_b128 v[8:11], v221 offset:2048
	ds_read_b128 v[12:15], v221 offset:3072
	ds_read_b128 v[16:19], v221 offset:4096
	ds_read_b128 v[20:23], v221 offset:5120
	ds_read_b128 v[24:27], v221 offset:6144
	ds_read_b128 v[28:31], v221 offset:7168
	ds_read_b128 v[32:35], v221 offset:8192
	ds_read_b128 v[36:39], v221 offset:9216
	ds_read_b128 v[40:43], v221 offset:10240
	ds_read_b128 v[44:47], v221 offset:11264
	ds_read_b128 v[48:51], v221 offset:12288
	ds_read_b128 v[52:55], v221 offset:13312
	ds_read_b128 v[56:59], v221 offset:14336
	ds_read_b128 v[60:63], v221 offset:15360
	s_add_u32 s8, s46, 0x13e00000
	s_addc_u32 s9, s47, 0
	v_lshlrev_b32_e32 v194, 1, v192
	s_add_u32 s2, s44, 0x1be00000
	s_waitcnt lgkmcnt(0)
	v_lshl_add_u64 v[66:67], s[4:5], 0, v[194:195]
	s_mov_b64 s[4:5], 0xfc00000
	s_addc_u32 s60, s45, 0
	v_lshl_add_u64 v[212:213], v[66:67], 0, s[4:5]
	v_lshl_add_u64 v[66:67], s[6:7], 0, v[194:195]
	s_mov_b64 s[4:5], 0xba00000
	s_ashr_i32 s21, s20, 31
	v_lshl_add_u64 v[214:215], v[66:67], 0, s[4:5]
	s_lshl_b64 s[4:5], s[20:21], 12
	v_and_b32_e32 v64, 63, v64
	s_add_u32 s4, s8, s4
	v_lshl_add_u64 v[202:203], s[8:9], 0, v[194:195]
	v_lshlrev_b32_e32 v194, 3, v64
	s_addc_u32 s5, s9, s5
	v_or_b32_e32 v204, 0x400, v192
	v_or_b32_e32 v206, 0x500, v192
	v_or_b32_e32 v208, 0x600, v192
	v_or_b32_e32 v210, 0x700, v192
	v_lshl_add_u64 v[216:217], s[4:5], 0, v[194:195]
	s_mov_b64 s[44:45], 0
	s_mov_b32 s61, s20
	s_branch .LBB0_961

; #define LAS __attribute__((address_space(3)))
; __device__ __forceinline__ void pass_post(const bf16* o16, const float* opart, const float* hlat, const float* hctx, const bf16* h16in, float* olat, float* octx, bf16* h16out, const float* gpost, const float* mod, int gt_off, ...
;     lds_vec(lp, gpost, tid); if (U) lds_vec(lp + 2048, gpre, tid);
; #pragma unroll
;     for (int vi = 0; vi < 3; ++vi) { lds_vec(lp + 4096 + (3 * vi) * 2048, mod + vi * 12288 + gt_off, tid);
;         if (U) { lds_vec(lp + 4096 + (3 * vi + 1) * 2048, modu + vi * 12288 + sh_off, tid); lds_vec(lp + 4096 + (3 * vi + 2) * 2048, modu + vi * 12288 + sc_off, tid); } }
;     __syncthreads();
;     for (int m0 = gw; m0 < nrows; m0 += 2 * NGW) {
;         int mr[2]; mr[0] = m0; mr[1] = m0 + NGW; const bool two = mr[1] < nrows; if (!two) mr[1] = m0;
;         f32x4 v[2][8], hh[2][8]; float ss[2];
; #pragma unroll
;         for (int r = 0; r < 2; ++r) { const int m = mr[r]; ss[r] = 0.f;
;             const float* hs = m < MLAT ? hlat + (size_t)m * DM : hctx + (size_t)(m - MLAT) * DM;
;             if (m < MLAT) { const bf16* orow = o16 + (size_t)m * DM;
; #pragma unroll
;                 for (int j = 0; j < 8; ++j) { const v2u raw = *(const v2u*)(orow + 256 * j + 4 * lane);
;                     v[r][j] = (f32x4){__uint_as_float(raw.x << 16), __uint_as_float(raw.x & 0xffff0000u), __uint_as_float(raw.y << 16), __uint_as_float(raw.y & 0xffff0000u)}; }
;             } else { const float* orow = opart + (size_t)(m - MLAT) * DM;
; #pragma unroll
;                 for (int j = 0; j < 8; ++j) { const int ci = 256 * j + 4 * lane;
;                     v[r][j] = (*(const f32x4*)(orow + ci) + *(const f32x4*)(orow + ci + (size_t)512 * DM)) + (*(const f32x4*)(orow + ci + (size_t)1024 * DM) + *(const f32x4*)(orow + ci + (size_t)1536 * DM)); } }
;             if (h16in) { const bf16* hrow = h16in + (size_t)m * DM;
.LBB0_1205:
	s_ashr_i32 s2, s2, 6
	v_readlane_b32 s4, v253, 2
	s_lshl_b32 s98, s2, 8
	s_add_i32 s18, s98, s4
	s_cmp_lt_i32 s18, s66
	s_waitcnt lgkmcnt(0)
	s_barrier
	s_cbranch_scc0 .LBB0_1226
	v_lshlrev_b32_e32 v2, 2, v32
	v_and_b32_e32 v112, 0xfc, v2
	v_lshlrev_b32_e32 v194, 1, v112
	v_lshl_add_u64 v[0:1], s[42:43], 0, v[194:195]
	s_mov_b64 s[4:5], 0xba00000
	v_lshl_add_u64 v[114:115], v[0:1], 0, s[4:5]
	v_lshl_add_u64 v[0:1], s[20:21], 0, v[194:195]
	s_mov_b64 s[4:5], 0xfc00000
	v_lshl_add_u64 v[116:117], v[0:1], 0, s[4:5]
	v_bfrev_b32_e32 v0, 0.5
	s_movk_i32 s4, 0x80
	v_lshl_add_u32 v181, v112, 2, 0
	s_add_u32 s2, s46, 0x21500000
	v_bitop3_b32 v113, v2, 4, v0 bitop3:0x6c
	v_bitop3_b32 v176, v2, 8, v0 bitop3:0x6c
	v_bitop3_b32 v177, v2, 16, v0 bitop3:0x6c
	v_bitop3_b32 v178, v2, 32, v0 bitop3:0x6c
	v_bitop3_b32 v179, v2, 64, v0 bitop3:0x6c
	v_bitop3_b32 v180, v2, s4, v0 bitop3:0x6c
	ds_read_b128 v[0:3], v181
	ds_read_b128 v[4:7], v181 offset:1024
	ds_read_b128 v[8:11], v181 offset:2048
	ds_read_b128 v[12:15], v181 offset:3072
	ds_read_b128 v[16:19], v181 offset:4096
	ds_read_b128 v[20:23], v181 offset:5120
	ds_read_b128 v[24:27], v181 offset:6144
	ds_read_b128 v[28:31], v181 offset:7168
	s_addc_u32 s60, s47, 0
	s_add_u32 s61, s52, 0xb600000
	s_addc_u32 s62, s53, 0
	s_ashr_i32 s19, s18, 31
	s_lshl_b64 s[4:5], s[18:19], 12
	s_add_u32 s20, s20, s4
	s_addc_u32 s21, s21, s5
	s_lshl_b64 s[6:7], s[18:19], 13
	s_add_u32 s63, s16, s6
	s_addc_u32 s64, s17, s7
	v_or_b32_e32 v34, 0x400, v112
	v_or_b32_e32 v36, 0x500, v112
	v_or_b32_e32 v38, 0x600, v112
	v_or_b32_e32 v40, 0x700, v112
	v_and_b32_e32 v32, 63, v32
	s_add_u32 s42, s42, s4
	v_lshl_add_u64 v[118:119], s[44:45], 0, v[194:195]
	v_lshlrev_b32_e32 v120, 3, v32
	v_mov_b32_e32 v121, v195
	s_addc_u32 s43, s43, s5
	s_mov_b64 s[44:45], 0
	v_lshlrev_b32_e32 v122, 2, v34
	v_lshlrev_b32_e32 v124, 2, v36
	v_lshlrev_b32_e32 v126, 2, v38
	v_lshlrev_b32_e32 v128, 2, v40
	s_mov_b32 s65, s18
	s_branch .LBB0_1208
